# XCD-local barriers after phases 1,6,7,8,9; norm and SGU items remapped so producers and consumers of each token tile share an XCD
# speedup vs baseline: 1.1861x; 1.0136x over previous
.LBB0_97:
	s_and_b32 s100, s63, 7
	s_lshl_b32 s100, s100, 6
	s_lshr_b32 s101, s63, 6
	s_lshl_b32 s101, s101, 3
	s_or_b32 s100, s100, s101
	s_bfe_u32 s101, s63, 0x30003
	s_or_b32 s99, s100, s101
	v_mov_b32_e32 v0, v207
	s_ashr_i32 s6, s99, 7
	v_ashrrev_i32_e32 v1, 31, v0
	s_mul_i32 s7, s6, 0x3000
	v_lshlrev_b64 v[2:3], 2, v[0:1]
	s_mul_hi_i32 s0, s6, 0x3000
	s_add_u32 s4, s24, s7
	v_lshl_add_u64 v[8:9], v[2:3], 0, s[34:35]
	s_addc_u32 s5, s25, s0
	v_lshl_add_u64 v[6:7], s[68:69], 0, v[8:9]
	s_add_i32 s0, s6, 4
	s_add_i32 s1, s7, 0xc000
	v_lshl_add_u64 v[4:5], s[68:69], 0, v[2:3]
	global_load_dword v1, v[6:7], off
	global_load_dword v32, v[4:5], off
	v_lshl_add_u64 v[12:13], s[4:5], 0, v[8:9]
	v_lshl_add_u64 v[6:7], s[4:5], 0, v[2:3]
	s_mul_hi_i32 s0, s0, 0x3000
	s_add_u32 s4, s24, s1
	s_addc_u32 s5, s25, s0
	s_add_i32 s0, s6, 8
	s_add_i32 s1, s7, 0x18000
	v_lshl_add_u64 v[14:15], s[4:5], 0, v[8:9]
	v_lshl_add_u64 v[10:11], s[4:5], 0, v[2:3]
	s_mul_hi_i32 s0, s0, 0x3000
	s_add_u32 s4, s24, s1
	s_addc_u32 s5, s25, s0
	s_add_i32 s0, s6, 12
	s_add_i32 s1, s7, 0x24000
	global_load_dword v42, v[12:13], off
	global_load_dword v43, v[6:7], off
	global_load_dword v44, v[14:15], off
	global_load_dword v45, v[10:11], off
	v_lshl_add_u64 v[14:15], s[4:5], 0, v[8:9]
	v_lshl_add_u64 v[12:13], s[4:5], 0, v[2:3]
	s_mul_hi_i32 s0, s0, 0x3000
	s_add_u32 s4, s24, s1
	s_addc_u32 s5, s25, s0
	s_add_i32 s0, s6, 16
	s_add_i32 s1, s7, 0x30000
	v_lshl_add_u64 v[16:17], s[4:5], 0, v[8:9]
	global_load_dword v46, v[14:15], off
	global_load_dword v47, v[12:13], off
	global_load_dword v57, v[16:17], off
	v_lshl_add_u64 v[14:15], s[4:5], 0, v[2:3]
	s_mul_hi_i32 s0, s0, 0x3000
	s_add_u32 s4, s24, s1
	s_addc_u32 s5, s25, s0
	s_add_i32 s0, s6, 20
	s_add_i32 s1, s7, 0x3c000
	v_lshl_add_u64 v[18:19], s[4:5], 0, v[8:9]
	v_lshl_add_u64 v[16:17], s[4:5], 0, v[2:3]
	s_mul_hi_i32 s0, s0, 0x3000
	s_add_u32 s4, s24, s1
	s_addc_u32 s5, s25, s0
	s_add_i32 s0, s6, 24
	s_add_i32 s1, s7, 0x48000
	global_load_dword v58, v[14:15], off
	global_load_dword v59, v[18:19], off
	global_load_dword v60, v[16:17], off
	v_lshl_add_u64 v[22:23], s[4:5], 0, v[8:9]
	v_lshl_add_u64 v[18:19], s[4:5], 0, v[2:3]
	s_mul_hi_i32 s0, s0, 0x3000
	s_add_u32 s4, s24, s1
	s_addc_u32 s5, s25, s0
	s_add_i32 s0, s6, 28
	s_add_i32 s1, s7, 0x54000
	v_lshl_add_u64 v[24:25], s[4:5], 0, v[8:9]
	v_lshl_add_u64 v[20:21], s[4:5], 0, v[2:3]
	s_mul_hi_i32 s0, s0, 0x3000
	s_add_u32 s4, s24, s1
	s_addc_u32 s5, s25, s0
	s_add_i32 s0, s6, 32
	s_add_i32 s1, s7, 0x60000
	global_load_dword v61, v[22:23], off
	global_load_dword v62, v[18:19], off
	global_load_dword v63, v[24:25], off
	global_load_dword v64, v[20:21], off
	v_lshl_add_u64 v[24:25], s[4:5], 0, v[8:9]
	v_lshl_add_u64 v[22:23], s[4:5], 0, v[2:3]
	s_mul_hi_i32 s0, s0, 0x3000
	s_add_u32 s4, s24, s1
	s_addc_u32 s5, s25, s0
	s_add_i32 s0, s6, 36
	s_add_i32 s1, s7, 0x6c000
	global_load_dword v65, v[24:25], off
	global_load_dword v66, v[22:23], off
	v_lshl_add_u64 v[28:29], s[4:5], 0, v[8:9]
	v_lshl_add_u64 v[24:25], s[4:5], 0, v[2:3]
	s_mul_hi_i32 s0, s0, 0x3000
	s_add_u32 s4, s24, s1
	s_addc_u32 s5, s25, s0
	s_add_i32 s0, s6, 40
	s_add_i32 s1, s7, 0x78000
	v_lshl_add_u64 v[30:31], s[4:5], 0, v[8:9]
	v_lshl_add_u64 v[26:27], s[4:5], 0, v[2:3]
	s_mul_hi_i32 s0, s0, 0x3000
	s_add_u32 s4, s24, s1
	s_addc_u32 s5, s25, s0
	s_add_i32 s0, s6, 44
	s_add_i32 s1, s7, 0x84000
	global_load_dword v67, v[28:29], off
	global_load_dword v68, v[24:25], off
	global_load_dword v69, v[30:31], off
	global_load_dword v70, v[26:27], off
	v_lshl_add_u64 v[30:31], s[4:5], 0, v[8:9]
	v_lshl_add_u64 v[28:29], s[4:5], 0, v[2:3]
	s_mul_hi_i32 s0, s0, 0x3000
	s_add_u32 s4, s24, s1
	s_addc_u32 s5, s25, s0
	s_add_i32 s0, s6, 48
	s_add_i32 s1, s7, 0x90000
	v_lshl_add_u64 v[34:35], s[4:5], 0, v[8:9]
	global_load_dword v71, v[30:31], off
	global_load_dword v72, v[28:29], off
	global_load_dword v73, v[34:35], off
	v_lshl_add_u64 v[30:31], s[4:5], 0, v[2:3]
	s_mul_hi_i32 s0, s0, 0x3000
	s_add_u32 s4, s24, s1
	s_addc_u32 s5, s25, s0
	v_lshl_add_u64 v[36:37], s[4:5], 0, v[8:9]
	v_lshl_add_u64 v[34:35], s[4:5], 0, v[2:3]
	global_load_dword v74, v[30:31], off
	global_load_dword v75, v[36:37], off
	global_load_dword v76, v[34:35], off
	s_add_i32 s0, s6, 52
	s_add_i32 s1, s7, 0x9c000
	s_mul_hi_i32 s0, s0, 0x3000
	s_add_u32 s4, s24, s1
	s_addc_u32 s5, s25, s0
	s_add_i32 s0, s6, 56
	s_add_i32 s1, s7, 0xa8000
	v_lshl_add_u64 v[38:39], s[4:5], 0, v[8:9]
	v_lshl_add_u64 v[36:37], s[4:5], 0, v[2:3]
	s_mul_hi_i32 s0, s0, 0x3000
	s_add_u32 s4, s24, s1
	s_addc_u32 s5, s25, s0
	v_lshl_add_u64 v[40:41], s[4:5], 0, v[8:9]
	global_load_dword v77, v[38:39], off
	global_load_dword v78, v[36:37], off
	s_nop 0
	global_load_dword v40, v[40:41], off
	s_nop 0
	global_load_dword v79, v[4:5], off offset:1024
	global_load_dword v80, v[4:5], off offset:2048
	global_load_dword v81, v[4:5], off offset:3072
	global_load_dword v82, v[6:7], off offset:1024
	global_load_dword v83, v[10:11], off offset:1024
	global_load_dword v84, v[6:7], off offset:2048
	global_load_dword v85, v[6:7], off offset:3072
	s_waitcnt vmcnt(35)
	v_add_f32_e32 v1, v1, v42
	s_waitcnt vmcnt(34)
	v_add_f32_e32 v32, v32, v43
	s_waitcnt vmcnt(33)
	v_add_f32_e32 v1, v1, v44
	s_waitcnt vmcnt(32)
	v_add_f32_e32 v32, v32, v45
	s_waitcnt vmcnt(31)
	v_add_f32_e32 v1, v1, v46
	s_waitcnt vmcnt(30)
	v_add_f32_e32 v32, v32, v47
	s_waitcnt vmcnt(29)
	v_add_f32_e32 v1, v1, v57
	s_add_i32 s6, s6, 60
	s_add_i32 s7, s7, 0xb4000
	s_waitcnt vmcnt(28)
	v_add_f32_e32 v32, v32, v58
	s_waitcnt vmcnt(27)
	v_add_f32_e32 v1, v1, v59
	s_waitcnt vmcnt(26)
	v_add_f32_e32 v32, v32, v60
	v_lshl_add_u64 v[38:39], s[4:5], 0, v[2:3]
	s_mul_hi_i32 s0, s6, 0x3000
	s_add_u32 s4, s24, s7
	s_addc_u32 s5, s25, s0
	v_lshl_add_u64 v[8:9], s[4:5], 0, v[8:9]
	global_load_dword v44, v[12:13], off offset:1024
	global_load_dword v45, v[10:11], off offset:2048
	global_load_dword v86, v[12:13], off offset:2048
	global_load_dword v87, v[12:13], off offset:3072
	global_load_dword v88, v[10:11], off offset:3072
	global_load_dword v46, v[14:15], off offset:1024
	global_load_dword v47, v[16:17], off offset:1024
	global_load_dword v57, v[14:15], off offset:2048
	global_load_dword v89, v[16:17], off offset:2048
	global_load_dword v90, v[14:15], off offset:3072
	global_load_dword v58, v[18:19], off offset:1024
	global_load_dword v59, v[18:19], off offset:2048
	global_load_dword v60, v[18:19], off offset:3072
	global_load_dword v91, v[16:17], off offset:3072
	v_add_co_u32_e32 v4, vcc, s39, v4
	s_mov_b32 s66, 0
	s_waitcnt vmcnt(39)
	v_add_f32_e32 v1, v1, v61
	s_waitcnt vmcnt(38)
	v_add_f32_e32 v32, v32, v62
	s_waitcnt vmcnt(37)
	v_add_f32_e32 v1, v1, v63
	s_waitcnt vmcnt(36)
	v_add_f32_e32 v32, v32, v64
	global_load_dword v61, v[20:21], off offset:1024
	global_load_dword v62, v[22:23], off offset:1024
	global_load_dword v63, v[20:21], off offset:2048
	global_load_dword v64, v[22:23], off offset:2048
	global_load_dword v92, v[22:23], off offset:3072
	global_load_dword v93, v[20:21], off offset:3072
	v_addc_co_u32_e32 v5, vcc, 0, v5, vcc
	v_add_co_u32_e32 v6, vcc, s39, v6
	s_mov_b64 s[40:41], -1
	s_waitcnt vmcnt(41)
	v_add_f32_e32 v1, v1, v65
	s_waitcnt vmcnt(40)
	v_add_f32_e32 v32, v32, v66
	global_load_dword v65, v[24:25], off offset:1024
	global_load_dword v66, v[26:27], off offset:1024
	global_load_dword v94, v[24:25], off offset:2048
	global_load_dword v95, v[24:25], off offset:3072
	v_addc_co_u32_e32 v7, vcc, 0, v7, vcc
	s_waitcnt vmcnt(43)
	v_add_f32_e32 v1, v1, v67
	s_waitcnt vmcnt(42)
	v_add_f32_e32 v32, v32, v68
	s_waitcnt vmcnt(41)
	v_add_f32_e32 v1, v1, v69
	s_waitcnt vmcnt(40)
	v_add_f32_e32 v32, v32, v70
	global_load_dword v67, v[28:29], off offset:1024
	global_load_dword v68, v[26:27], off offset:2048
	global_load_dword v69, v[28:29], off offset:2048
	global_load_dword v70, v[28:29], off offset:3072
	global_load_dword v96, v[26:27], off offset:3072
	s_waitcnt vmcnt(44)
	v_add_f32_e32 v1, v1, v71
	s_waitcnt vmcnt(43)
	v_add_f32_e32 v32, v32, v72
	s_waitcnt vmcnt(42)
	v_add_f32_e32 v1, v1, v73
	global_load_dword v71, v[30:31], off offset:1024
	global_load_dword v72, v[34:35], off offset:1024
	global_load_dword v73, v[30:31], off offset:2048
	global_load_dword v97, v[34:35], off offset:2048
	global_load_dword v98, v[30:31], off offset:3072
	s_waitcnt vmcnt(46)
	v_add_f32_e32 v32, v32, v74
	s_waitcnt vmcnt(45)
	v_add_f32_e32 v1, v1, v75
	s_waitcnt vmcnt(44)
	v_add_f32_e32 v32, v32, v76
	global_load_dword v74, v[38:39], off
	global_load_dword v75, v[36:37], off offset:1024
	global_load_dword v76, v[36:37], off offset:2048
	global_load_dword v99, v[36:37], off offset:3072
	global_load_dword v100, v[34:35], off offset:3072
	s_waitcnt vmcnt(48)
	v_add_f32_e32 v1, v1, v77
	s_waitcnt vmcnt(47)
	v_add_f32_e32 v32, v32, v78
	s_waitcnt vmcnt(46)
	v_add_f32_e32 v1, v1, v40
	v_lshl_add_u64 v[40:41], s[4:5], 0, v[2:3]
	global_load_dword v77, v[8:9], off
	global_load_dword v78, v[40:41], off
	v_add_co_u32_e32 v8, vcc, s39, v10
	global_load_dword v102, v[4:5], off offset:1024
	s_nop 0
	v_addc_co_u32_e32 v9, vcc, 0, v11, vcc
	v_add_co_u32_e32 v10, vcc, s39, v12
	v_lshl_add_u64 v[2:3], s[64:65], 0, v[2:3]
	s_nop 0
	v_addc_co_u32_e32 v11, vcc, 0, v13, vcc
	v_add_co_u32_e32 v12, vcc, s39, v14
	global_load_dword v101, v[2:3], off
	s_nop 0
	v_addc_co_u32_e32 v13, vcc, 0, v15, vcc
	v_add_co_u32_e32 v14, vcc, s39, v16
	global_load_dword v103, v[6:7], off offset:1024
	global_load_dword v104, v[8:9], off offset:1024
	global_load_dword v105, v[10:11], off offset:1024
	v_addc_co_u32_e32 v15, vcc, 0, v17, vcc
	v_add_co_u32_e32 v16, vcc, s39, v18
	s_waitcnt vmcnt(11)
	v_add_f32_e32 v32, v32, v74
	v_addc_co_u32_e32 v17, vcc, 0, v19, vcc
	v_add_co_u32_e32 v18, vcc, s39, v20
	global_load_dword v106, v[12:13], off offset:1024
	global_load_dword v107, v[14:15], off offset:1024
	global_load_dword v108, v[16:17], off offset:1024
	v_addc_co_u32_e32 v19, vcc, 0, v21, vcc
	v_add_co_u32_e32 v20, vcc, s39, v22
	s_waitcnt vmcnt(9)
	v_add_f32_e32 v1, v1, v77
	v_addc_co_u32_e32 v21, vcc, 0, v23, vcc
	v_add_co_u32_e32 v22, vcc, s39, v24
	global_load_dword v109, v[18:19], off offset:1024
	global_load_dword v110, v[20:21], off offset:1024
	v_addc_co_u32_e32 v23, vcc, 0, v25, vcc
	v_add_co_u32_e32 v24, vcc, s39, v26
	s_waitcnt vmcnt(10)
	v_add_f32_e32 v32, v32, v78
	v_addc_co_u32_e32 v25, vcc, 0, v27, vcc
	v_add_co_u32_e32 v26, vcc, s39, v28
	v_add_f32_e32 v1, 1.0, v1
	s_nop 0
	v_addc_co_u32_e32 v27, vcc, 0, v29, vcc
	v_add_co_u32_e32 v28, vcc, s39, v30
	global_load_dword v111, v[22:23], off offset:1024
	global_load_dword v112, v[24:25], off offset:1024
	global_load_dword v113, v[26:27], off offset:1024
	v_addc_co_u32_e32 v29, vcc, 0, v31, vcc
	v_add_co_u32_e32 v30, vcc, s39, v34
	s_waitcnt vmcnt(11)
	v_mul_f32_e32 v1, v1, v101
	v_addc_co_u32_e32 v31, vcc, 0, v35, vcc
	v_add_co_u32_e32 v34, vcc, s39, v36
	v_lshlrev_b32_e32 v101, 2, v0
	s_nop 0
	v_addc_co_u32_e32 v35, vcc, 0, v37, vcc
	v_add_co_u32_e32 v36, vcc, s39, v38
	global_load_dword v114, v[28:29], off offset:1024
	global_load_dword v115, v[30:31], off offset:1024
	global_load_dword v116, v[34:35], off offset:1024
	v_addc_co_u32_e32 v37, vcc, 0, v39, vcc
	v_add_co_u32_e32 v42, vcc, s39, v40
	global_load_dword v117, v[36:37], off offset:1024
	global_load_dword v118, v[38:39], off offset:1024
	v_addc_co_u32_e32 v43, vcc, 0, v41, vcc
	global_load_dword v119, v[42:43], off offset:1024
	global_load_dword v120, v[40:41], off offset:1024
	global_load_dword v74, v[2:3], off offset:1024
	global_load_dword v121, v[4:5], off offset:2048
	global_load_dword v122, v[6:7], off offset:2048
	global_load_dword v123, v[8:9], off offset:2048
	global_load_dword v124, v[10:11], off offset:2048
	global_load_dword v125, v[12:13], off offset:2048
	global_load_dword v126, v[38:39], off offset:2048
	global_load_dword v127, v[40:41], off offset:2048
	s_nop 0
	global_load_dword v40, v[40:41], off offset:3072
	s_nop 0
	global_load_dword v38, v[38:39], off offset:3072
	v_ashrrev_i32_e32 v0, 3, v0
	global_load_dword v39, v[14:15], off offset:2048
	global_load_dword v41, v[16:17], off offset:2048
	global_load_dword v77, v[18:19], off offset:2048
	global_load_dword v78, v[20:21], off offset:2048
	global_load_dword v128, v[22:23], off offset:2048
	global_load_dword v129, v[2:3], off offset:2048
	s_nop 0
	global_load_dword v2, v[2:3], off offset:3072
	v_and_b32_e32 v0, -8, v0
	global_load_dword v3, v[24:25], off offset:2048
	global_load_dword v130, v[26:27], off offset:2048
	global_load_dword v131, v[28:29], off offset:2048
	global_load_dword v132, v[30:31], off offset:2048
	global_load_dword v133, v[34:35], off offset:2048
	global_load_dword v134, v[36:37], off offset:2048
	s_nop 0
	global_load_dword v4, v[4:5], off offset:3072
	s_nop 0
	global_load_dword v5, v[8:9], off offset:3072
	s_nop 0
	global_load_dword v6, v[6:7], off offset:3072
	s_waitcnt vmcnt(43)
	v_add_f32_e32 v7, v102, v103
	global_load_dword v8, v[42:43], off offset:2048
	s_nop 0
	global_load_dword v14, v[14:15], off offset:3072
	s_nop 0
	global_load_dword v12, v[12:13], off offset:3072
	s_nop 0
	global_load_dword v10, v[10:11], off offset:3072
	s_nop 0
	global_load_dword v11, v[20:21], off offset:3072
	global_load_dword v13, v[18:19], off offset:3072
	global_load_dword v15, v[16:17], off offset:3072
	s_nop 0
	global_load_dword v16, v[24:25], off offset:3072
	global_load_dword v17, v[22:23], off offset:3072
	global_load_dword v18, v[30:31], off offset:3072
	global_load_dword v19, v[28:29], off offset:3072
	global_load_dword v20, v[26:27], off offset:3072
	global_load_dword v21, v[42:43], off offset:3072
	s_nop 0
	global_load_dword v22, v[36:37], off offset:3072
	global_load_dword v23, v[34:35], off offset:3072
	s_waitcnt vmcnt(57)
	v_add_f32_e32 v7, v7, v104
	s_waitcnt vmcnt(56)
	v_add_f32_e32 v7, v7, v105
	v_add_f32_e32 v9, v79, v82
	v_add_f32_e32 v9, v9, v83
	v_add_f32_e32 v9, v9, v44
	v_add_f32_e32 v9, v9, v46
	v_add_f32_e32 v9, v9, v47
	v_add_f32_e32 v9, v9, v58
	v_add_f32_e32 v9, v9, v61
	v_add_f32_e32 v9, v9, v62
	v_add_f32_e32 v9, v9, v65
	v_add_f32_e32 v9, v9, v66
	s_waitcnt vmcnt(55)
	v_add_f32_e32 v7, v7, v106
	s_waitcnt vmcnt(54)
	v_add_f32_e32 v7, v7, v107
	s_waitcnt vmcnt(53)
	v_add_f32_e32 v7, v7, v108
	v_add_f32_e32 v9, v9, v67
	v_add_f32_e32 v9, v9, v71
	v_add_f32_e32 v9, v9, v72
	v_add_f32_e32 v9, v9, v75
	v_cmp_lt_i32_e32 vcc, v51, v50
	v_and_b32_e32 v36, 0xfc, v101
	s_waitcnt vmcnt(52)
	v_add_f32_e32 v7, v7, v109
	s_waitcnt vmcnt(51)
	v_add_f32_e32 v7, v7, v110
	s_waitcnt vmcnt(50)
	v_add_f32_e32 v7, v7, v111
	s_waitcnt vmcnt(49)
	v_add_f32_e32 v7, v7, v112
	s_waitcnt vmcnt(48)
	v_add_f32_e32 v7, v7, v113
	s_waitcnt vmcnt(47)
	v_add_f32_e32 v7, v7, v114
	s_waitcnt vmcnt(46)
	v_add_f32_e32 v7, v7, v115
	s_waitcnt vmcnt(45)
	v_add_f32_e32 v7, v7, v116
	s_waitcnt vmcnt(44)
	v_add_f32_e32 v7, v7, v117
	s_waitcnt vmcnt(43)
	v_add_f32_e32 v9, v9, v118
	s_waitcnt vmcnt(42)
	v_add_f32_e32 v7, v7, v119
	v_add_f32_e32 v7, 1.0, v7
	s_waitcnt vmcnt(40)
	v_mul_f32_e32 v7, v7, v74
	v_add_f32_e32 v9, v9, v120
	ds_write2st64_b32 v101, v1, v7 offset1:4
	ds_write2st64_b32 v101, v32, v9 offset0:16 offset1:20
	s_waitcnt vmcnt(38)
	v_add_f32_e32 v1, v121, v122
	s_waitcnt vmcnt(37)
	v_add_f32_e32 v1, v1, v123
	v_add_f32_e32 v7, v80, v84
	s_waitcnt vmcnt(36)
	v_add_f32_e32 v1, v1, v124
	v_add_f32_e32 v7, v7, v45
	s_waitcnt vmcnt(15)
	v_add_f32_e32 v4, v4, v6
	v_add_f32_e32 v4, v4, v5
	v_add_f32_e32 v6, v81, v85
	s_waitcnt vmcnt(11)
	v_add_f32_e32 v4, v4, v10
	v_add_f32_e32 v1, v1, v125
	v_add_f32_e32 v5, v6, v88
	v_add_f32_e32 v4, v4, v12
	v_add_f32_e32 v7, v7, v86
	v_add_f32_e32 v1, v1, v39
	v_add_f32_e32 v5, v5, v87
	v_add_f32_e32 v4, v4, v14
	v_add_f32_e32 v7, v7, v57
	v_add_f32_e32 v1, v1, v41
	v_add_f32_e32 v5, v5, v90
	s_waitcnt vmcnt(8)
	v_add_f32_e32 v4, v4, v15
	v_add_f32_e32 v7, v7, v89
	v_add_f32_e32 v1, v1, v77
	v_add_f32_e32 v5, v5, v91
	v_add_f32_e32 v4, v4, v13
	v_add_f32_e32 v7, v7, v59
	v_add_f32_e32 v1, v1, v78
	v_add_f32_e32 v5, v5, v60
	v_add_f32_e32 v4, v4, v11
	v_add_f32_e32 v7, v7, v63
	v_add_f32_e32 v1, v1, v128
	v_add_f32_e32 v5, v5, v93
	s_waitcnt vmcnt(6)
	v_add_f32_e32 v4, v4, v17
	v_add_f32_e32 v7, v7, v64
	v_add_f32_e32 v1, v1, v3
	v_add_f32_e32 v5, v5, v92
	v_add_f32_e32 v4, v4, v16
	v_add_f32_e32 v7, v7, v94
	v_add_f32_e32 v1, v1, v130
	v_add_f32_e32 v5, v5, v95
	s_waitcnt vmcnt(3)
	v_add_f32_e32 v4, v4, v20
	v_add_f32_e32 v3, v7, v68
	v_add_f32_e32 v1, v1, v131
	v_add_f32_e32 v5, v5, v96
	v_add_f32_e32 v4, v4, v19
	v_add_f32_e32 v3, v3, v69
	v_add_f32_e32 v1, v1, v132
	v_add_f32_e32 v5, v5, v70
	v_add_f32_e32 v4, v4, v18
	v_add_f32_e32 v3, v3, v73
	v_add_f32_e32 v1, v1, v133
	v_add_f32_e32 v5, v5, v98
	s_waitcnt vmcnt(0)
	v_add_f32_e32 v4, v4, v23
	v_lshl_add_u32 v57, s99, 5, v0
	v_cndmask_b32_e32 v0, v49, v51, vcc
	v_cmp_lt_i32_e32 vcc, v52, v50
	v_add_f32_e32 v3, v3, v97
	v_add_f32_e32 v1, v1, v134
	v_add_f32_e32 v5, v5, v100
	v_add_f32_e32 v4, v4, v22
	v_lshlrev_b32_e32 v58, 2, v0
	v_cndmask_b32_e32 v0, v49, v52, vcc
	v_cmp_lt_i32_e32 vcc, v53, v50
	v_add_f32_e32 v3, v3, v76
	v_add_f32_e32 v1, v1, v8
	v_add_f32_e32 v5, v5, v99
	v_add_f32_e32 v4, v4, v21
	v_lshlrev_b32_e32 v59, 2, v0
	v_cndmask_b32_e32 v0, v49, v53, vcc
	v_cmp_lt_i32_e32 vcc, v54, v50
	v_add_f32_e32 v3, v3, v126
	v_add_f32_e32 v1, 1.0, v1
	v_add_f32_e32 v5, v5, v38
	v_add_f32_e32 v4, 1.0, v4
	v_lshlrev_b32_e32 v60, 2, v0
	v_cndmask_b32_e32 v0, v49, v54, vcc
	v_cmp_lt_i32_e32 vcc, v55, v50
	v_add_f32_e32 v3, v3, v127
	v_mul_f32_e32 v1, v1, v129
	v_add_f32_e32 v5, v5, v40
	v_mul_f32_e32 v2, v4, v2
	v_lshlrev_b32_e32 v32, 2, v36
	v_lshlrev_b32_e32 v61, 2, v0
	v_cndmask_b32_e32 v0, v49, v55, vcc
	ds_write2st64_b32 v101, v1, v2 offset0:8 offset1:12
	ds_write2st64_b32 v101, v3, v5 offset0:24 offset1:28
	s_waitcnt lgkmcnt(0)
	s_barrier
	v_lshlrev_b32_e32 v62, 2, v0
	ds_read_b128 v[0:3], v32
	ds_read_b128 v[4:7], v32 offset:1024
	ds_read_b128 v[8:11], v32 offset:4096
	ds_read_b128 v[12:15], v32 offset:5120
	ds_read_b128 v[16:19], v32 offset:2048
	ds_read_b128 v[20:23], v32 offset:3072
	ds_read_b128 v[24:27], v32 offset:6144
	ds_read_b128 v[28:31], v32 offset:7168
	v_cmp_lt_i32_e32 vcc, v56, v50
	v_lshl_add_u64 v[34:35], s[60:61], 0, v[32:33]
	v_lshlrev_b32_e32 v32, 1, v36
	v_cndmask_b32_e32 v37, v49, v56, vcc
	v_lshlrev_b32_e32 v63, 2, v37
	v_lshl_add_u64 v[36:37], s[30:31], 0, v[32:33]

.LBB0_132:
	s_andn2_saveexec_b64 s[8:9], s[8:9]
	s_cbranch_execz .LBB0_152
	s_mov_b64 s[8:9], exec
	s_branch .LBB0_149
	buffer_wbl2 sc1
	s_waitcnt lgkmcnt(0)
	s_waitcnt vmcnt(0)
	v_mbcnt_lo_u32_b32 v1, s8, 0
	v_mbcnt_hi_u32_b32 v1, s9, v1
	v_cmp_eq_u32_e32 vcc, 0, v1
	s_and_saveexec_b64 s[10:11], vcc
	s_cbranch_execz .LBB0_135
	s_bcnt1_i32_b64 s0, s[8:9]
	v_mov_b32_e32 v2, 0xfd2c000
	v_mov_b32_e32 v3, s0
	global_atomic_add v2, v2, v3, s[58:59] offset:1024 sc0

.LBB0_2013:
	s_or_b64 exec, exec, s[18:19]
	s_and_b32 s19, s99, 7
	v_ashrrev_i32_e32 v1, 1, v0
	s_lshl_b32 s18, s19, 7
	v_and_b32_e32 v76, 0xffffffe0, v1
	v_and_b32_e32 v101, 31, v0
	v_add_u32_e32 v1, s18, v76
	v_or_b32_e32 v4, v1, v101
	s_lshl_b64 s[0:1], s[16:17], 23
	v_ashrrev_i32_e32 v5, 31, v4
	s_add_u32 s0, s2, s0
	s_addc_u32 s1, s9, s1
	v_lshlrev_b64 v[2:3], 13, v[4:5]
	v_lshl_add_u64 v[2:3], s[0:1], 0, v[2:3]
	s_lshl_b32 s0, s19, 15
	s_add_u32 s0, s20, s0
	v_lshrrev_b32_e32 v0, 2, v0
	s_addc_u32 s1, s21, 0
	s_lshl_b32 s6, s6, 1
	v_and_b32_e32 v12, 8, v0
	v_lshl_add_u64 v[2:3], v[2:3], 0, s[6:7]
	v_lshlrev_b32_e32 v94, 1, v12
	v_lshl_add_u64 v[104:105], v[2:3], 0, v[94:95]
	s_waitcnt lgkmcnt(0)
	s_barrier
	global_load_dwordx4 v[0:3], v[104:105], off
	v_lshlrev_b64 v[4:5], 2, v[4:5]
	v_lshl_add_u64 v[6:7], s[48:49], 0, v[4:5]
	v_lshl_add_u64 v[4:5], s[50:51], 0, v[4:5]
	global_load_dword v98, v[6:7], off
	global_load_dword v100, v[4:5], off
	v_mov_b32_e32 v5, v95
	v_lshlrev_b32_e32 v4, 8, v101
	v_lshl_add_u64 v[108:109], s[0:1], 0, v[94:95]
	v_lshl_add_u64 v[32:33], v[108:109], 0, v[4:5]
	v_add_co_u32_e32 v64, vcc, s28, v32
	v_lshlrev_b32_e32 v99, 2, v12
	s_nop 0
	v_addc_co_u32_e32 v65, vcc, 0, v33, vcc
	v_add_co_u32_e32 v90, vcc, s29, v32
	global_load_dwordx4 v[4:7], v[32:33], off
	global_load_dwordx4 v[8:11], v[64:65], off
	v_addc_co_u32_e32 v91, vcc, 0, v33, vcc
	ds_read_b128 v[12:15], v99
	ds_read_b128 v[16:19], v99 offset:16
	global_load_dwordx4 v[20:23], v[90:91], off
	global_load_dwordx4 v[66:69], v[104:105], off offset:32
	v_add_co_u32_e32 v110, vcc, s30, v32
	ds_read_b128 v[24:27], v99 offset:512
	ds_read_b128 v[28:31], v99 offset:528
	v_addc_co_u32_e32 v111, vcc, 0, v33, vcc
	global_load_dwordx4 v[70:73], v[110:111], off
	global_load_dwordx4 v[78:81], v[32:33], off offset:32
	global_load_dwordx4 v[82:85], v[64:65], off offset:32
	global_load_dwordx4 v[86:89], v[90:91], off offset:32
	ds_read_b128 v[112:115], v99 offset:64
	ds_read_b128 v[116:119], v99 offset:80
	ds_read_b128 v[120:123], v99 offset:576
	ds_read_b128 v[124:127], v99 offset:592
	global_load_dwordx4 v[128:131], v[110:111], off offset:32
	v_ashrrev_i32_e32 v77, 31, v76
	v_or_b32_e32 v102, s14, v101
	v_lshlrev_b64 v[106:107], 1, v[76:77]
	s_mul_i32 s16, s15, 0x1800
	v_mad_u64_u32 v[76:77], s[0:1], v102, s31, v[96:97]
	s_lshl_b32 s6, s19, 8
	v_add_u32_e32 v77, s16, v77
	v_lshl_add_u64 v[76:77], v[76:77], 0, s[6:7]
	v_lshl_add_u64 v[76:77], v[76:77], 0, v[106:107]
	v_lshl_add_u64 v[76:77], v[76:77], 0, v[94:95]
	s_add_u32 s0, s22, s6
	s_addc_u32 s1, s23, 0
	v_mov_b32_e32 v103, s15
	s_add_i32 s34, s34, s42
	s_add_i32 s24, s24, s25
	s_cmpk_lt_i32 s34, 0x400
	s_waitcnt vmcnt(11)
	v_lshlrev_b32_e32 v32, 16, v0
	v_and_b32_e32 v33, 0xffff0000, v0
	v_lshlrev_b32_e32 v0, 16, v1
	v_and_b32_e32 v1, 0xffff0000, v1
	v_lshlrev_b32_e32 v34, 16, v2
	v_and_b32_e32 v35, 0xffff0000, v2
	v_lshlrev_b32_e32 v2, 16, v3
	v_and_b32_e32 v3, 0xffff0000, v3
	s_waitcnt lgkmcnt(7)
	v_pk_add_f32 v[12:13], v[32:33], v[12:13] neg_lo:[0,1] neg_hi:[0,1]
	v_pk_add_f32 v[0:1], v[0:1], v[14:15] neg_lo:[0,1] neg_hi:[0,1]
	s_waitcnt lgkmcnt(6)
	v_pk_add_f32 v[14:15], v[34:35], v[16:17] neg_lo:[0,1] neg_hi:[0,1]
	v_pk_add_f32 v[2:3], v[2:3], v[18:19] neg_lo:[0,1] neg_hi:[0,1]
	s_waitcnt lgkmcnt(5)
	v_pk_mul_f32 v[12:13], v[24:25], v[12:13]
	v_pk_mul_f32 v[0:1], v[0:1], v[26:27]
	s_waitcnt lgkmcnt(4)
	v_pk_mul_f32 v[14:15], v[14:15], v[28:29]
	v_pk_mul_f32 v[2:3], v[2:3], v[30:31]
	s_waitcnt vmcnt(9)
	v_pk_fma_f32 v[12:13], v[98:99], v[12:13], v[100:101] op_sel_hi:[0,1,0]
	v_pk_fma_f32 v[16:17], v[98:99], v[0:1], v[100:101] op_sel_hi:[0,1,0]
	v_pk_fma_f32 v[14:15], v[98:99], v[14:15], v[100:101] op_sel_hi:[0,1,0]
	v_pk_fma_f32 v[18:19], v[98:99], v[2:3], v[100:101] op_sel_hi:[0,1,0]
	v_cvt_pk_bf16_f32 v0, v12, v13
	v_cvt_pk_bf16_f32 v1, v16, v17
	v_cvt_pk_bf16_f32 v2, v14, v15
	v_cvt_pk_bf16_f32 v3, v18, v19
	s_waitcnt vmcnt(8)
	s_nop 0
	v_mfma_f32_32x32x16_bf16 v[48:63], v[0:3], v[4:7], 0
	s_waitcnt vmcnt(5)
	v_lshlrev_b32_e32 v4, 16, v66
	v_and_b32_e32 v5, 0xffff0000, v66
	v_lshlrev_b32_e32 v66, 16, v67
	v_and_b32_e32 v67, 0xffff0000, v67
	s_waitcnt lgkmcnt(3)
	v_pk_add_f32 v[4:5], v[4:5], v[112:113] neg_lo:[0,1] neg_hi:[0,1]
	v_pk_add_f32 v[66:67], v[66:67], v[114:115] neg_lo:[0,1] neg_hi:[0,1]
	s_waitcnt lgkmcnt(1)
	v_pk_mul_f32 v[4:5], v[120:121], v[4:5]
	v_pk_mul_f32 v[66:67], v[66:67], v[122:123]
	v_mfma_f32_32x32x16_bf16 v[32:47], v[0:3], v[8:11], 0
	v_fma_f32 v74, v98, v4, v100
	v_fma_f32 v75, v98, v5, v100
	global_load_dwordx4 v[112:115], v[104:105], off offset:96
	v_mfma_f32_32x32x16_bf16 v[16:31], v[0:3], v[20:23], 0
	s_waitcnt vmcnt(5)
	v_mfma_f32_32x32x16_bf16 v[0:15], v[0:3], v[70:73], 0
	v_fma_f32 v70, v98, v66, v100
	v_fma_f32 v71, v98, v67, v100
	v_lshlrev_b32_e32 v66, 16, v68
	v_and_b32_e32 v67, 0xffff0000, v68
	v_add_f32_e64 v66, v66, -v116
	v_add_f32_e64 v67, v67, -v117
	s_waitcnt lgkmcnt(0)
	v_pk_mul_f32 v[66:67], v[66:67], v[124:125]
	s_nop 0
	v_pk_fma_f32 v[72:73], v[98:99], v[66:67], v[100:101] op_sel_hi:[0,1,0]
	v_lshlrev_b32_e32 v66, 16, v69
	v_and_b32_e32 v67, 0xffff0000, v69
	v_pk_add_f32 v[66:67], v[66:67], v[118:119] neg_lo:[0,1] neg_hi:[0,1]
	v_cvt_pk_bf16_f32 v68, v72, v73
	v_pk_mul_f32 v[66:67], v[66:67], v[126:127]
	ds_read_b128 v[116:119], v99 offset:656
	v_pk_fma_f32 v[92:93], v[98:99], v[66:67], v[100:101] op_sel_hi:[0,1,0]
	v_cvt_pk_bf16_f32 v67, v70, v71
	global_load_dwordx4 v[70:73], v[104:105], off offset:64
	v_cvt_pk_bf16_f32 v66, v74, v75
	v_cvt_pk_bf16_f32 v69, v92, v93
	s_waitcnt vmcnt(1)
	v_lshlrev_b32_e32 v92, 16, v113
	v_mfma_f32_32x32x16_bf16 v[48:63], v[66:69], v[78:81], v[48:63]
	global_load_dwordx4 v[78:81], v[64:65], off offset:64
	v_and_b32_e32 v93, 0xffff0000, v113
	s_waitcnt vmcnt(1)
	v_lshlrev_b32_e32 v74, 16, v70
	v_mfma_f32_32x32x16_bf16 v[32:47], v[66:69], v[82:85], v[32:47]
	ds_read_b128 v[82:85], v99 offset:640
	v_and_b32_e32 v75, 0xffff0000, v70
	v_lshlrev_b32_e32 v70, 16, v71
	v_and_b32_e32 v71, 0xffff0000, v71
	v_mfma_f32_32x32x16_bf16 v[16:31], v[66:69], v[86:89], v[16:31]
	ds_read_b128 v[86:89], v99 offset:144
	v_mfma_f32_32x32x16_bf16 v[0:15], v[66:69], v[128:131], v[0:15]
	ds_read_b128 v[66:69], v99 offset:128
	s_waitcnt lgkmcnt(0)
	v_add_f32_e64 v68, v70, -v68
	v_add_f32_e64 v69, v71, -v69
	v_lshlrev_b32_e32 v70, 16, v72
	v_and_b32_e32 v71, 0xffff0000, v72
	v_lshlrev_b32_e32 v72, 16, v73
	v_and_b32_e32 v73, 0xffff0000, v73
	v_pk_add_f32 v[66:67], v[74:75], v[66:67] neg_lo:[0,1] neg_hi:[0,1]
	v_pk_add_f32 v[70:71], v[70:71], v[86:87] neg_lo:[0,1] neg_hi:[0,1]
	v_pk_add_f32 v[72:73], v[72:73], v[88:89] neg_lo:[0,1] neg_hi:[0,1]
	v_pk_mul_f32 v[66:67], v[82:83], v[66:67]
	v_pk_mul_f32 v[68:69], v[68:69], v[84:85]
	v_pk_mul_f32 v[70:71], v[70:71], v[116:117]
	v_pk_mul_f32 v[72:73], v[72:73], v[118:119]
	v_pk_fma_f32 v[66:67], v[98:99], v[66:67], v[100:101] op_sel_hi:[0,1,0]
	v_pk_fma_f32 v[68:69], v[98:99], v[68:69], v[100:101] op_sel_hi:[0,1,0]
	v_pk_fma_f32 v[70:71], v[98:99], v[70:71], v[100:101] op_sel_hi:[0,1,0]
	v_pk_fma_f32 v[72:73], v[98:99], v[72:73], v[100:101] op_sel_hi:[0,1,0]
	v_cvt_pk_bf16_f32 v82, v66, v67
	v_cvt_pk_bf16_f32 v83, v68, v69
	v_cvt_pk_bf16_f32 v84, v70, v71
	v_cvt_pk_bf16_f32 v85, v72, v73
	global_load_dwordx4 v[72:75], v[64:65], off offset:96
	global_load_dwordx4 v[68:71], v[90:91], off offset:64
	s_nop 0
	global_load_dwordx4 v[64:67], v[90:91], off offset:96
	s_waitcnt vmcnt(3)
	v_mfma_f32_32x32x16_bf16 v[32:47], v[82:85], v[78:81], v[32:47]
	s_waitcnt vmcnt(1)
	v_mfma_f32_32x32x16_bf16 v[16:31], v[82:85], v[68:71], v[16:31]
	global_load_dwordx4 v[86:89], v[110:111], off offset:64
	global_load_dwordx4 v[68:71], v[110:111], off offset:96
	global_load_dwordx4 v[78:81], v[104:105], off offset:128
	ds_read_b128 v[120:123], v99 offset:208
	ds_read_b128 v[116:119], v99 offset:704
	ds_read_b128 v[130:133], v99 offset:272
	ds_read_b128 v[134:137], v99 offset:784
	s_waitcnt vmcnt(2)
	v_mfma_f32_32x32x16_bf16 v[0:15], v[82:85], v[86:89], v[0:15]
	ds_read_b128 v[86:89], v99 offset:192
	v_lshlrev_b32_e32 v82, 16, v112
	v_and_b32_e32 v83, 0xffff0000, v112
	s_waitcnt lgkmcnt(0)
	v_add_f32_e64 v86, v82, -v86
	v_add_f32_e64 v87, v83, -v87
	ds_read_b128 v[82:85], v99 offset:720
	v_pk_add_f32 v[88:89], v[92:93], v[88:89] neg_lo:[0,1] neg_hi:[0,1]
	v_lshlrev_b32_e32 v92, 16, v114
	v_and_b32_e32 v93, 0xffff0000, v114
	v_pk_add_f32 v[92:93], v[92:93], v[120:121] neg_lo:[0,1] neg_hi:[0,1]
	v_pk_mul_f32 v[86:87], v[116:117], v[86:87]
	s_waitcnt lgkmcnt(0)
	v_pk_mul_f32 v[82:83], v[92:93], v[82:83]
	v_lshlrev_b32_e32 v92, 16, v115
	v_and_b32_e32 v93, 0xffff0000, v115
	v_pk_add_f32 v[92:93], v[92:93], v[122:123] neg_lo:[0,1] neg_hi:[0,1]
	v_pk_mul_f32 v[88:89], v[88:89], v[118:119]
	v_pk_mul_f32 v[84:85], v[92:93], v[84:85]
	v_add_co_u32_e32 v92, vcc, s33, v76
	v_pk_fma_f32 v[86:87], v[98:99], v[86:87], v[100:101] op_sel_hi:[0,1,0]
	s_nop 0
	v_addc_co_u32_e32 v93, vcc, 0, v77, vcc
	v_pk_fma_f32 v[88:89], v[98:99], v[88:89], v[100:101] op_sel_hi:[0,1,0]
	v_pk_fma_f32 v[82:83], v[98:99], v[82:83], v[100:101] op_sel_hi:[0,1,0]
	global_load_dwordx4 v[118:121], v[92:93], off
	global_load_dwordx4 v[122:125], v[76:77], off offset:32
	v_pk_fma_f32 v[92:93], v[98:99], v[84:85], v[100:101] op_sel_hi:[0,1,0]
	v_cvt_pk_bf16_f32 v84, v86, v87
	v_cvt_pk_bf16_f32 v85, v88, v89
	v_cvt_pk_bf16_f32 v86, v82, v83
	v_cvt_pk_bf16_f32 v87, v92, v93
	global_load_dwordx4 v[114:117], v[76:77], off
	s_nop 0
	v_mfma_f32_32x32x16_bf16 v[16:31], v[84:87], v[64:67], v[16:31]
	v_or_b32_e32 v64, s18, v101
	v_lshlrev_b32_e32 v112, 2, v64
	global_load_dword v146, v112, s[54:55]
	ds_read_b128 v[64:67], v99 offset:256
	s_waitcnt vmcnt(0)
	v_pk_add_f32 v[48:49], v[48:49], v[146:147] op_sel_hi:[1,0]
	v_mfma_f32_32x32x16_bf16 v[32:47], v[84:87], v[72:75], v[32:47]
	v_lshl_add_u64 v[72:73], v[76:77], 0, s[10:11]
	global_load_dwordx4 v[126:129], v[72:73], off offset:32
	v_lshlrev_b32_e32 v72, 16, v78
	v_and_b32_e32 v73, 0xffff0000, v78
	s_waitcnt lgkmcnt(0)
	v_pk_add_f32 v[64:65], v[72:73], v[64:65] neg_lo:[0,1] neg_hi:[0,1]
	v_mov_b32_e32 v113, v117
	s_nop 1
	v_permlane32_swap_b32_e32 v115, v113
	v_mfma_f32_32x32x16_bf16 v[0:15], v[84:87], v[68:71], v[0:15]
	ds_read_b128 v[68:71], v99 offset:768
	v_mov_b32_e32 v117, v121
	global_load_dwordx4 v[82:85], v[104:105], off offset:160
	s_nop 0
	v_permlane32_swap_b32_e32 v119, v117
	s_waitcnt lgkmcnt(0)
	v_pk_mul_f32 v[64:65], v[68:69], v[64:65]
	v_pk_add_f32 v[50:51], v[50:51], v[146:147] op_sel_hi:[1,0]
	v_pk_fma_f32 v[148:149], v[98:99], v[64:65], v[100:101] op_sel_hi:[0,1,0]
	v_lshlrev_b32_e32 v64, 16, v79
	v_and_b32_e32 v65, 0xffff0000, v79
	v_pk_add_f32 v[64:65], v[64:65], v[66:67] neg_lo:[0,1] neg_hi:[0,1]
	v_pk_add_f32 v[52:53], v[52:53], v[146:147] op_sel_hi:[1,0]
	v_pk_mul_f32 v[64:65], v[64:65], v[70:71]
	global_load_dwordx4 v[138:141], v[90:91], off offset:128
	global_load_dwordx4 v[86:89], v[90:91], off offset:160
	global_load_dwordx4 v[142:145], v[110:111], off offset:128
	s_nop 0
	global_load_dwordx4 v[90:93], v[110:111], off offset:160
	global_load_dwordx4 v[76:79], v[104:105], off offset:192
	global_load_dwordx4 v[68:71], v[104:105], off offset:224
	v_pk_fma_f32 v[150:151], v[98:99], v[64:65], v[100:101] op_sel_hi:[0,1,0]
	v_lshlrev_b32_e32 v64, 16, v80
	v_and_b32_e32 v65, 0xffff0000, v80
	v_pk_add_f32 v[64:65], v[64:65], v[130:131] neg_lo:[0,1] neg_hi:[0,1]
	v_or_b32_e32 v80, 0x60, v101
	v_pk_mul_f32 v[64:65], v[64:65], v[134:135]
	v_pk_add_f32 v[54:55], v[54:55], v[146:147] op_sel_hi:[1,0]
	v_pk_fma_f32 v[130:131], v[98:99], v[64:65], v[100:101] op_sel_hi:[0,1,0]
	v_mov_b32_e32 v101, v116
	v_lshlrev_b32_e32 v64, 8, v80
	v_mov_b32_e32 v65, v95
	v_permlane32_swap_b32_e32 v114, v101
	v_mov_b32_e32 v116, v120
	v_lshl_add_u64 v[64:65], v[108:109], 0, v[64:65]
	s_nop 0
	v_permlane32_swap_b32_e32 v118, v116
	v_lshlrev_b32_e32 v108, 16, v114
	v_and_b32_e32 v109, 0xffff0000, v114
	global_load_dwordx4 v[72:75], v[110:111], off offset:192
	s_nop 0
	global_load_dwordx4 v[64:67], v[64:65], off offset:224
	v_lshlrev_b32_e32 v110, 16, v118
	v_and_b32_e32 v111, 0xffff0000, v118
	v_pk_mul_f32 v[48:49], v[48:49], v[108:109]
	v_lshlrev_b32_e32 v108, 16, v115
	v_and_b32_e32 v109, 0xffff0000, v115
	v_pk_mul_f32 v[48:49], v[48:49], v[110:111]
	v_lshlrev_b32_e32 v110, 16, v119
	v_and_b32_e32 v111, 0xffff0000, v119
	v_pk_mul_f32 v[50:51], v[50:51], v[108:109]
	v_cvt_pk_bf16_f32 v48, v48, v49
	v_pk_mul_f32 v[50:51], v[50:51], v[110:111]
	v_lshlrev_b32_e32 v108, 16, v116
	v_cvt_pk_bf16_f32 v49, v50, v51
	v_lshlrev_b32_e32 v50, 16, v101
	v_and_b32_e32 v51, 0xffff0000, v101
	v_and_b32_e32 v109, 0xffff0000, v116
	v_pk_mul_f32 v[50:51], v[52:53], v[50:51]
	v_lshlrev_b32_e32 v52, 16, v113
	v_and_b32_e32 v53, 0xffff0000, v113
	v_mov_b32_e32 v120, v124
	v_pk_mul_f32 v[50:51], v[50:51], v[108:109]
	v_lshlrev_b32_e32 v108, 16, v117
	v_and_b32_e32 v109, 0xffff0000, v117
	v_pk_mul_f32 v[52:53], v[54:55], v[52:53]
	v_permlane32_swap_b32_e32 v122, v120
	v_pk_mul_f32 v[52:53], v[52:53], v[108:109]
	v_mov_b32_e32 v121, v125
	v_cvt_pk_bf16_f32 v50, v50, v51
	v_cvt_pk_bf16_f32 v51, v52, v53
	v_lshlrev_b32_e32 v52, 16, v122
	v_and_b32_e32 v53, 0xffff0000, v122
	v_pk_add_f32 v[56:57], v[56:57], v[146:147] op_sel_hi:[1,0]
	v_permlane32_swap_b32_e32 v123, v121
	v_pk_mul_f32 v[52:53], v[56:57], v[52:53]
	v_pk_add_f32 v[58:59], v[58:59], v[146:147] op_sel_hi:[1,0]
	v_lshl_add_u64 v[104:105], s[0:1], 0, v[106:107]
	s_waitcnt vmcnt(9)
	v_mov_b32_e32 v124, v128
	s_nop 1
	v_permlane32_swap_b32_e32 v126, v124
	v_mov_b32_e32 v125, v129
	v_lshlrev_b32_e32 v54, 16, v126
	v_and_b32_e32 v55, 0xffff0000, v126
	v_permlane32_swap_b32_e32 v127, v125
	v_pk_mul_f32 v[52:53], v[52:53], v[54:55]
	v_lshlrev_b32_e32 v54, 16, v123
	v_and_b32_e32 v55, 0xffff0000, v123
	v_lshlrev_b32_e32 v56, 16, v127
	v_and_b32_e32 v57, 0xffff0000, v127
	v_pk_mul_f32 v[54:55], v[58:59], v[54:55]
	v_cvt_pk_bf16_f32 v52, v52, v53
	v_pk_mul_f32 v[54:55], v[54:55], v[56:57]
	v_pk_add_f32 v[58:59], v[60:61], v[146:147] op_sel_hi:[1,0]
	v_cvt_pk_bf16_f32 v53, v54, v55
	v_lshlrev_b32_e32 v54, 16, v120
	v_and_b32_e32 v55, 0xffff0000, v120
	v_lshlrev_b32_e32 v56, 16, v124
	v_and_b32_e32 v57, 0xffff0000, v124
	v_pk_mul_f32 v[54:55], v[58:59], v[54:55]
	v_pk_add_f32 v[60:61], v[62:63], v[146:147] op_sel_hi:[1,0]
	v_pk_mul_f32 v[54:55], v[54:55], v[56:57]
	v_lshlrev_b32_e32 v56, 16, v121
	v_and_b32_e32 v57, 0xffff0000, v121
	v_lshlrev_b32_e32 v58, 16, v125
	v_and_b32_e32 v59, 0xffff0000, v125
	v_pk_mul_f32 v[56:57], v[60:61], v[56:57]
	v_permlane32_swap_b32_e32 v48, v50
	v_pk_mul_f32 v[56:57], v[56:57], v[58:59]
	v_lshlrev_b64 v[58:59], 11, v[102:103]
	v_lshl_add_u64 v[58:59], v[104:105], 0, v[58:59]
	v_permlane32_swap_b32_e32 v49, v51
	v_lshl_add_u64 v[60:61], v[58:59], 0, v[94:95]
	v_or_b32_e32 v126, 32, v102
	global_store_dwordx4 v[60:61], v[48:51], off
	v_cvt_pk_bf16_f32 v54, v54, v55
	v_cvt_pk_bf16_f32 v55, v56, v57
	v_mad_u64_u32 v[48:49], s[0:1], v126, s31, v[96:97]
	v_add_u32_e32 v49, s16, v49
	v_lshl_add_u64 v[48:49], v[48:49], 0, s[6:7]
	v_lshl_add_u64 v[48:49], v[48:49], 0, v[106:107]
	v_lshl_add_u64 v[62:63], v[48:49], 0, v[94:95]
	global_load_dwordx4 v[48:51], v[62:63], off
	v_add_co_u32_e32 v56, vcc, s33, v62
	v_permlane32_swap_b32_e32 v52, v54
	v_permlane32_swap_b32_e32 v53, v55
	v_addc_co_u32_e32 v57, vcc, 0, v63, vcc
	global_store_dwordx4 v[60:61], v[52:55], off offset:32
	global_load_dwordx4 v[56:59], v[56:57], off
	v_lshlrev_b32_e32 v134, 16, v81
	global_load_dword v128, v112, s[54:55] offset:128
	global_load_dwordx4 v[52:55], v[62:63], off offset:32
	v_and_b32_e32 v135, 0xffff0000, v81
	v_pk_add_f32 v[60:61], v[134:135], v[132:133] neg_lo:[0,1] neg_hi:[0,1]
	v_cvt_pk_bf16_f32 v108, v148, v149
	v_pk_mul_f32 v[60:61], v[60:61], v[136:137]
	v_cvt_pk_bf16_f32 v109, v150, v151
	v_pk_fma_f32 v[114:115], v[98:99], v[60:61], v[100:101] op_sel_hi:[0,1,0]
	v_lshl_add_u64 v[60:61], v[62:63], 0, s[10:11]
	global_load_dwordx4 v[60:63], v[60:61], off offset:32
	v_cvt_pk_bf16_f32 v110, v130, v131
	v_cvt_pk_bf16_f32 v111, v114, v115
	s_waitcnt vmcnt(15)
	v_lshlrev_b32_e32 v122, 16, v82
	v_and_b32_e32 v123, 0xffff0000, v82
	s_waitcnt vmcnt(14)
	v_mfma_f32_32x32x16_bf16 v[16:31], v[108:111], v[138:141], v[16:31]
	ds_read_b128 v[118:121], v99 offset:336
	ds_read_b128 v[114:117], v99 offset:832
	v_lshlrev_b32_e32 v82, 16, v83
	v_and_b32_e32 v83, 0xffff0000, v83
	v_mov_b32_e32 v127, s15
	v_or_b32_e32 v102, 64, v102
	s_waitcnt vmcnt(5)
	v_mov_b32_e32 v81, v50
	v_mfma_f32_32x32x16_bf16 v[0:15], v[108:111], v[142:145], v[0:15]
	ds_read_b128 v[108:111], v99 offset:320
	v_permlane32_swap_b32_e32 v48, v81
	v_lshlrev_b32_e32 v50, 16, v48
	s_waitcnt lgkmcnt(0)
	v_pk_add_f32 v[108:109], v[122:123], v[108:109] neg_lo:[0,1] neg_hi:[0,1]
	ds_read_b128 v[122:125], v99 offset:848
	v_pk_add_f32 v[82:83], v[82:83], v[110:111] neg_lo:[0,1] neg_hi:[0,1]
	v_lshlrev_b32_e32 v110, 16, v84
	v_and_b32_e32 v111, 0xffff0000, v84
	v_pk_add_f32 v[110:111], v[110:111], v[118:119] neg_lo:[0,1] neg_hi:[0,1]
	v_pk_mul_f32 v[108:109], v[114:115], v[108:109]
	v_pk_mul_f32 v[82:83], v[82:83], v[116:117]
	s_waitcnt lgkmcnt(0)
	v_pk_mul_f32 v[110:111], v[110:111], v[122:123]
	v_pk_fma_f32 v[108:109], v[98:99], v[108:109], v[100:101] op_sel_hi:[0,1,0]
	v_pk_fma_f32 v[82:83], v[98:99], v[82:83], v[100:101] op_sel_hi:[0,1,0]
	v_pk_fma_f32 v[110:111], v[98:99], v[110:111], v[100:101] op_sel_hi:[0,1,0]
	v_mov_b32_e32 v101, v51
	s_nop 1
	v_permlane32_swap_b32_e32 v49, v101
	s_waitcnt vmcnt(3)
	v_permlane32_swap_b32_e32 v56, v58
	v_permlane32_swap_b32_e32 v57, v59
	v_and_b32_e32 v51, 0xffff0000, v48
	s_waitcnt vmcnt(2)
	v_pk_add_f32 v[32:33], v[32:33], v[128:129] op_sel_hi:[1,0]
	v_lshlrev_b32_e32 v48, 16, v49
	v_and_b32_e32 v49, 0xffff0000, v49
	v_pk_add_f32 v[34:35], v[34:35], v[128:129] op_sel_hi:[1,0]
	s_waitcnt vmcnt(1)
	v_mov_b32_e32 v113, v54
	v_mov_b32_e32 v114, v55
	v_lshlrev_b32_e32 v54, 16, v56
	v_and_b32_e32 v55, 0xffff0000, v56
	v_pk_mul_f32 v[32:33], v[32:33], v[50:51]
	v_lshlrev_b32_e32 v50, 16, v57
	v_and_b32_e32 v51, 0xffff0000, v57
	v_pk_mul_f32 v[34:35], v[34:35], v[48:49]
	v_pk_mul_f32 v[32:33], v[32:33], v[54:55]
	v_pk_mul_f32 v[34:35], v[34:35], v[50:51]
	v_cvt_pk_bf16_f32 v32, v32, v33
	v_cvt_pk_bf16_f32 v33, v34, v35
	v_lshlrev_b32_e32 v34, 16, v81
	v_and_b32_e32 v35, 0xffff0000, v81
	v_pk_add_f32 v[36:37], v[36:37], v[128:129] op_sel_hi:[1,0]
	v_lshlrev_b32_e32 v48, 16, v58
	v_and_b32_e32 v49, 0xffff0000, v58
	v_pk_mul_f32 v[34:35], v[36:37], v[34:35]
	v_lshlrev_b32_e32 v36, 16, v101
	v_and_b32_e32 v37, 0xffff0000, v101
	v_pk_add_f32 v[38:39], v[38:39], v[128:129] op_sel_hi:[1,0]
	v_pk_mul_f32 v[34:35], v[34:35], v[48:49]
	v_lshlrev_b32_e32 v48, 16, v59
	v_and_b32_e32 v49, 0xffff0000, v59
	v_pk_mul_f32 v[36:37], v[38:39], v[36:37]
	v_permlane32_swap_b32_e32 v52, v113
	v_pk_mul_f32 v[36:37], v[36:37], v[48:49]
	s_waitcnt vmcnt(0)
	v_permlane32_swap_b32_e32 v60, v62
	v_cvt_pk_bf16_f32 v34, v34, v35
	v_cvt_pk_bf16_f32 v35, v36, v37
	v_lshlrev_b32_e32 v36, 16, v52
	v_and_b32_e32 v37, 0xffff0000, v52
	v_pk_add_f32 v[40:41], v[40:41], v[128:129] op_sel_hi:[1,0]
	v_permlane32_swap_b32_e32 v53, v114
	v_lshlrev_b32_e32 v38, 16, v60
	v_and_b32_e32 v39, 0xffff0000, v60
	v_pk_mul_f32 v[36:37], v[40:41], v[36:37]
	v_permlane32_swap_b32_e32 v61, v63
	v_pk_mul_f32 v[36:37], v[36:37], v[38:39]
	v_lshlrev_b32_e32 v38, 16, v53
	v_and_b32_e32 v39, 0xffff0000, v53
	v_pk_add_f32 v[42:43], v[42:43], v[128:129] op_sel_hi:[1,0]
	v_lshlrev_b32_e32 v40, 16, v61
	v_and_b32_e32 v41, 0xffff0000, v61
	v_pk_mul_f32 v[38:39], v[42:43], v[38:39]
	v_cvt_pk_bf16_f32 v36, v36, v37
	v_pk_mul_f32 v[38:39], v[38:39], v[40:41]
	v_pk_add_f32 v[42:43], v[44:45], v[128:129] op_sel_hi:[1,0]
	v_cvt_pk_bf16_f32 v37, v38, v39
	v_lshlrev_b32_e32 v38, 16, v113
	v_and_b32_e32 v39, 0xffff0000, v113
	v_lshlrev_b32_e32 v40, 16, v62
	v_and_b32_e32 v41, 0xffff0000, v62
	v_pk_mul_f32 v[38:39], v[42:43], v[38:39]
	v_pk_add_f32 v[44:45], v[46:47], v[128:129] op_sel_hi:[1,0]
	v_pk_mul_f32 v[38:39], v[38:39], v[40:41]
	v_lshlrev_b32_e32 v40, 16, v114
	v_and_b32_e32 v41, 0xffff0000, v114
	v_lshlrev_b32_e32 v42, 16, v63
	v_and_b32_e32 v43, 0xffff0000, v63
	v_pk_mul_f32 v[40:41], v[44:45], v[40:41]
	v_permlane32_swap_b32_e32 v32, v34
	v_pk_mul_f32 v[40:41], v[40:41], v[42:43]
	v_lshlrev_b64 v[42:43], 11, v[126:127]
	v_lshl_add_u64 v[42:43], v[104:105], 0, v[42:43]
	v_permlane32_swap_b32_e32 v33, v35
	v_lshl_add_u64 v[44:45], v[42:43], 0, v[94:95]
	global_store_dwordx4 v[44:45], v[32:35], off
	v_cvt_pk_bf16_f32 v38, v38, v39
	v_cvt_pk_bf16_f32 v39, v40, v41
	v_mad_u64_u32 v[32:33], s[0:1], v102, s31, v[96:97]
	v_add_u32_e32 v33, s16, v33
	v_lshl_add_u64 v[32:33], v[32:33], 0, s[6:7]
	v_lshlrev_b32_e32 v84, 16, v85
	v_lshl_add_u64 v[32:33], v[32:33], 0, v[106:107]
	v_permlane32_swap_b32_e32 v36, v38
	v_permlane32_swap_b32_e32 v37, v39
	v_and_b32_e32 v85, 0xffff0000, v85
	v_lshl_add_u64 v[46:47], v[32:33], 0, v[94:95]
	global_store_dwordx4 v[44:45], v[36:39], off offset:32
	v_pk_add_f32 v[44:45], v[84:85], v[120:121] neg_lo:[0,1] neg_hi:[0,1]
	global_load_dwordx4 v[32:35], v[46:47], off
	global_load_dwordx4 v[36:39], v[46:47], off offset:32
	v_add_co_u32_e32 v40, vcc, s33, v46
	v_pk_mul_f32 v[44:45], v[44:45], v[124:125]
	s_nop 0
	v_addc_co_u32_e32 v41, vcc, 0, v47, vcc
	v_pk_fma_f32 v[52:53], v[98:99], v[44:45], v[100:101] op_sel_hi:[0,1,0]
	global_load_dwordx4 v[40:43], v[40:41], off
	v_cvt_pk_bf16_f32 v51, v52, v53
	global_load_dword v52, v112, s[54:55] offset:256
	v_lshl_add_u64 v[44:45], v[46:47], 0, s[10:11]
	global_load_dwordx4 v[44:47], v[44:45], off offset:32
	v_cvt_pk_bf16_f32 v48, v108, v109
	v_cvt_pk_bf16_f32 v49, v82, v83
	v_cvt_pk_bf16_f32 v50, v110, v111
	v_lshlrev_b32_e32 v54, 16, v76
	s_waitcnt vmcnt(4)
	v_mov_b32_e32 v53, v34
	v_mfma_f32_32x32x16_bf16 v[16:31], v[48:51], v[86:89], v[16:31]
	v_mov_b32_e32 v55, v35
	v_permlane32_swap_b32_e32 v32, v53
	s_nop 0
	v_permlane32_swap_b32_e32 v33, v55
	v_lshlrev_b32_e32 v34, 16, v32
	s_waitcnt vmcnt(2)
	v_permlane32_swap_b32_e32 v40, v42
	v_permlane32_swap_b32_e32 v41, v43
	v_and_b32_e32 v35, 0xffff0000, v32
	s_waitcnt vmcnt(1)
	s_nop 1
	v_pk_add_f32 v[16:17], v[16:17], v[52:53] op_sel_hi:[1,0]
	v_lshlrev_b32_e32 v32, 16, v33
	v_and_b32_e32 v33, 0xffff0000, v33
	v_pk_add_f32 v[18:19], v[18:19], v[52:53] op_sel_hi:[1,0]
	v_mov_b32_e32 v56, v38
	v_mov_b32_e32 v57, v39
	v_lshlrev_b32_e32 v38, 16, v40
	v_and_b32_e32 v39, 0xffff0000, v40
	v_pk_mul_f32 v[16:17], v[16:17], v[34:35]
	v_lshlrev_b32_e32 v34, 16, v41
	v_and_b32_e32 v35, 0xffff0000, v41
	v_pk_mul_f32 v[18:19], v[18:19], v[32:33]
	v_pk_mul_f32 v[16:17], v[16:17], v[38:39]
	v_pk_mul_f32 v[18:19], v[18:19], v[34:35]
	v_cvt_pk_bf16_f32 v16, v16, v17
	v_cvt_pk_bf16_f32 v17, v18, v19
	v_lshlrev_b32_e32 v18, 16, v53
	v_and_b32_e32 v19, 0xffff0000, v53
	v_pk_add_f32 v[20:21], v[20:21], v[52:53] op_sel_hi:[1,0]
	v_lshlrev_b32_e32 v32, 16, v42
	v_and_b32_e32 v33, 0xffff0000, v42
	v_pk_mul_f32 v[18:19], v[20:21], v[18:19]
	v_lshlrev_b32_e32 v20, 16, v55
	v_and_b32_e32 v21, 0xffff0000, v55
	v_pk_add_f32 v[22:23], v[22:23], v[52:53] op_sel_hi:[1,0]
	v_pk_mul_f32 v[18:19], v[18:19], v[32:33]
	v_lshlrev_b32_e32 v32, 16, v43
	v_and_b32_e32 v33, 0xffff0000, v43
	v_pk_mul_f32 v[20:21], v[22:23], v[20:21]
	v_permlane32_swap_b32_e32 v36, v56
	v_pk_mul_f32 v[20:21], v[20:21], v[32:33]
	s_waitcnt vmcnt(0)
	v_permlane32_swap_b32_e32 v44, v46
	v_cvt_pk_bf16_f32 v18, v18, v19
	v_cvt_pk_bf16_f32 v19, v20, v21
	v_lshlrev_b32_e32 v20, 16, v36
	v_and_b32_e32 v21, 0xffff0000, v36
	v_pk_add_f32 v[24:25], v[24:25], v[52:53] op_sel_hi:[1,0]
	v_permlane32_swap_b32_e32 v37, v57
	v_lshlrev_b32_e32 v22, 16, v44
	v_and_b32_e32 v23, 0xffff0000, v44
	v_pk_mul_f32 v[20:21], v[24:25], v[20:21]
	v_permlane32_swap_b32_e32 v45, v47
	v_pk_mul_f32 v[20:21], v[20:21], v[22:23]
	v_lshlrev_b32_e32 v22, 16, v37
	v_and_b32_e32 v23, 0xffff0000, v37
	v_pk_add_f32 v[26:27], v[26:27], v[52:53] op_sel_hi:[1,0]
	v_lshlrev_b32_e32 v24, 16, v45
	v_and_b32_e32 v25, 0xffff0000, v45
	v_pk_mul_f32 v[22:23], v[26:27], v[22:23]
	v_cvt_pk_bf16_f32 v20, v20, v21
	v_pk_mul_f32 v[22:23], v[22:23], v[24:25]
	v_pk_add_f32 v[26:27], v[28:29], v[52:53] op_sel_hi:[1,0]
	v_cvt_pk_bf16_f32 v21, v22, v23
	v_lshlrev_b32_e32 v22, 16, v56
	v_and_b32_e32 v23, 0xffff0000, v56
	v_lshlrev_b32_e32 v24, 16, v46
	v_and_b32_e32 v25, 0xffff0000, v46
	v_pk_mul_f32 v[22:23], v[26:27], v[22:23]
	v_pk_add_f32 v[28:29], v[30:31], v[52:53] op_sel_hi:[1,0]
	v_pk_mul_f32 v[22:23], v[22:23], v[24:25]
	v_lshlrev_b32_e32 v24, 16, v57
	v_and_b32_e32 v25, 0xffff0000, v57
	v_lshlrev_b32_e32 v26, 16, v47
	v_and_b32_e32 v27, 0xffff0000, v47
	v_pk_mul_f32 v[24:25], v[28:29], v[24:25]
	v_permlane32_swap_b32_e32 v16, v18
	v_pk_mul_f32 v[24:25], v[24:25], v[26:27]
	v_lshlrev_b64 v[26:27], 11, v[102:103]
	v_lshl_add_u64 v[26:27], v[104:105], 0, v[26:27]
	v_permlane32_swap_b32_e32 v17, v19
	v_lshl_add_u64 v[28:29], v[26:27], 0, v[94:95]
	v_or_b32_e32 v102, s14, v80
	global_store_dwordx4 v[28:29], v[16:19], off
	v_mfma_f32_32x32x16_bf16 v[0:15], v[48:51], v[90:93], v[0:15]
	ds_read_b128 v[48:51], v99 offset:384
	v_mad_u64_u32 v[16:17], s[0:1], v102, s31, v[96:97]
	v_add_u32_e32 v17, s16, v17
	v_lshl_add_u64 v[16:17], v[16:17], 0, s[6:7]
	v_lshl_add_u64 v[16:17], v[16:17], 0, v[106:107]
	v_cvt_pk_bf16_f32 v22, v22, v23
	v_lshl_add_u64 v[36:37], v[16:17], 0, v[94:95]
	v_cvt_pk_bf16_f32 v23, v24, v25
	global_load_dwordx4 v[16:19], v[36:37], off
	v_add_co_u32_e32 v24, vcc, s33, v36
	v_permlane32_swap_b32_e32 v20, v22
	v_permlane32_swap_b32_e32 v21, v23
	v_addc_co_u32_e32 v25, vcc, 0, v37, vcc
	global_store_dwordx4 v[28:29], v[20:23], off offset:32
	v_and_b32_e32 v55, 0xffff0000, v76
	global_load_dwordx4 v[24:27], v[24:25], off
	s_waitcnt lgkmcnt(0)
	v_pk_add_f32 v[44:45], v[54:55], v[48:49] neg_lo:[0,1] neg_hi:[0,1]
	global_load_dwordx4 v[20:23], v[36:37], off offset:32
	ds_read_b128 v[28:31], v99 offset:896
	ds_read_b128 v[32:35], v99 offset:400
	global_load_dword v48, v112, s[54:55] offset:384
	v_lshl_add_u64 v[36:37], v[36:37], 0, s[10:11]
	global_load_dwordx4 v[36:39], v[36:37], off offset:32
	ds_read_b128 v[40:43], v99 offset:912
	s_waitcnt lgkmcnt(2)
	v_pk_mul_f32 v[28:29], v[28:29], v[44:45]
	v_lshlrev_b32_e32 v44, 16, v77
	v_and_b32_e32 v45, 0xffff0000, v77
	v_pk_add_f32 v[44:45], v[44:45], v[50:51] neg_lo:[0,1] neg_hi:[0,1]
	v_pk_fma_f32 v[28:29], v[98:99], v[28:29], v[100:101] op_sel_hi:[0,1,0]
	v_pk_mul_f32 v[30:31], v[44:45], v[30:31]
	v_lshlrev_b32_e32 v44, 16, v78
	v_and_b32_e32 v45, 0xffff0000, v78
	s_waitcnt lgkmcnt(1)
	v_pk_add_f32 v[32:33], v[44:45], v[32:33] neg_lo:[0,1] neg_hi:[0,1]
	v_pk_fma_f32 v[30:31], v[98:99], v[30:31], v[100:101] op_sel_hi:[0,1,0]
	s_waitcnt lgkmcnt(0)
	v_pk_mul_f32 v[32:33], v[32:33], v[40:41]
	v_lshlrev_b32_e32 v40, 16, v79
	v_and_b32_e32 v41, 0xffff0000, v79
	v_pk_add_f32 v[34:35], v[40:41], v[34:35] neg_lo:[0,1] neg_hi:[0,1]
	v_pk_fma_f32 v[32:33], v[98:99], v[32:33], v[100:101] op_sel_hi:[0,1,0]
	v_pk_mul_f32 v[34:35], v[34:35], v[42:43]
	v_cvt_pk_bf16_f32 v28, v28, v29
	v_pk_fma_f32 v[34:35], v[98:99], v[34:35], v[100:101] op_sel_hi:[0,1,0]
	v_cvt_pk_bf16_f32 v29, v30, v31
	v_cvt_pk_bf16_f32 v30, v32, v33
	v_cvt_pk_bf16_f32 v31, v34, v35
	ds_read_b128 v[32:35], v99 offset:960
	v_lshlrev_b32_e32 v44, 16, v68
	v_mfma_f32_32x32x16_bf16 v[0:15], v[28:31], v[72:75], v[0:15]
	ds_read_b128 v[28:31], v99 offset:448
	ds_read_b128 v[40:43], v99 offset:464
	v_and_b32_e32 v45, 0xffff0000, v68
	s_waitcnt lgkmcnt(1)
	v_add_f32_e64 v28, v44, -v28
	v_add_f32_e64 v29, v45, -v29
	ds_read_b128 v[44:47], v99 offset:976
	v_pk_mul_f32 v[28:29], v[32:33], v[28:29]
	v_lshlrev_b32_e32 v32, 16, v69
	v_and_b32_e32 v33, 0xffff0000, v69
	v_pk_add_f32 v[30:31], v[32:33], v[30:31] neg_lo:[0,1] neg_hi:[0,1]
	v_lshlrev_b32_e32 v32, 16, v70
	v_pk_mul_f32 v[30:31], v[30:31], v[34:35]
	v_and_b32_e32 v33, 0xffff0000, v70
	v_lshlrev_b32_e32 v34, 16, v71
	v_and_b32_e32 v35, 0xffff0000, v71
	s_waitcnt lgkmcnt(1)
	v_pk_add_f32 v[32:33], v[32:33], v[40:41] neg_lo:[0,1] neg_hi:[0,1]
	v_pk_add_f32 v[34:35], v[34:35], v[42:43] neg_lo:[0,1] neg_hi:[0,1]
	s_waitcnt lgkmcnt(0)
	v_pk_mul_f32 v[32:33], v[32:33], v[44:45]
	v_pk_mul_f32 v[34:35], v[34:35], v[46:47]
	v_pk_fma_f32 v[28:29], v[98:99], v[28:29], v[100:101] op_sel_hi:[0,1,0]
	v_pk_fma_f32 v[30:31], v[98:99], v[30:31], v[100:101] op_sel_hi:[0,1,0]
	v_pk_fma_f32 v[32:33], v[98:99], v[32:33], v[100:101] op_sel_hi:[0,1,0]
	v_pk_fma_f32 v[34:35], v[98:99], v[34:35], v[100:101] op_sel_hi:[0,1,0]
	v_cvt_pk_bf16_f32 v28, v28, v29
	v_cvt_pk_bf16_f32 v29, v30, v31
	v_cvt_pk_bf16_f32 v30, v32, v33
	v_cvt_pk_bf16_f32 v31, v34, v35
	s_waitcnt vmcnt(3)
	v_permlane32_swap_b32_e32 v24, v26
	v_mfma_f32_32x32x16_bf16 v[0:15], v[28:31], v[64:67], v[0:15]
	v_mov_b32_e32 v28, v18
	v_mov_b32_e32 v29, v19
	s_nop 0
	v_permlane32_swap_b32_e32 v16, v28
	v_permlane32_swap_b32_e32 v17, v29
	v_permlane32_swap_b32_e32 v25, v27
	v_lshlrev_b32_e32 v18, 16, v16
	v_and_b32_e32 v19, 0xffff0000, v16
	s_waitcnt vmcnt(1)
	s_nop 2
	v_pk_add_f32 v[0:1], v[0:1], v[48:49] op_sel_hi:[1,0]
	v_lshlrev_b32_e32 v16, 16, v17
	v_and_b32_e32 v17, 0xffff0000, v17
	v_pk_add_f32 v[2:3], v[2:3], v[48:49] op_sel_hi:[1,0]
	v_mov_b32_e32 v30, v22
	v_mov_b32_e32 v31, v23
	v_lshlrev_b32_e32 v22, 16, v24
	v_and_b32_e32 v23, 0xffff0000, v24
	v_pk_mul_f32 v[0:1], v[0:1], v[18:19]
	v_lshlrev_b32_e32 v18, 16, v25
	v_and_b32_e32 v19, 0xffff0000, v25
	v_pk_mul_f32 v[2:3], v[2:3], v[16:17]
	v_pk_mul_f32 v[0:1], v[0:1], v[22:23]
	v_pk_mul_f32 v[2:3], v[2:3], v[18:19]
	v_cvt_pk_bf16_f32 v0, v0, v1
	v_cvt_pk_bf16_f32 v1, v2, v3
	v_lshlrev_b32_e32 v2, 16, v28
	v_and_b32_e32 v3, 0xffff0000, v28
	v_pk_add_f32 v[4:5], v[4:5], v[48:49] op_sel_hi:[1,0]
	v_lshlrev_b32_e32 v16, 16, v26
	v_and_b32_e32 v17, 0xffff0000, v26
	v_pk_mul_f32 v[2:3], v[4:5], v[2:3]
	v_lshlrev_b32_e32 v4, 16, v29
	v_and_b32_e32 v5, 0xffff0000, v29
	v_pk_add_f32 v[6:7], v[6:7], v[48:49] op_sel_hi:[1,0]
	v_pk_mul_f32 v[2:3], v[2:3], v[16:17]
	v_lshlrev_b32_e32 v16, 16, v27
	v_and_b32_e32 v17, 0xffff0000, v27
	v_pk_mul_f32 v[4:5], v[6:7], v[4:5]
	v_permlane32_swap_b32_e32 v20, v30
	s_waitcnt vmcnt(0)
	v_mov_b32_e32 v32, v38
	v_pk_mul_f32 v[4:5], v[4:5], v[16:17]
	s_nop 0
	v_permlane32_swap_b32_e32 v36, v32
	v_cvt_pk_bf16_f32 v2, v2, v3
	v_cvt_pk_bf16_f32 v3, v4, v5
	v_lshlrev_b32_e32 v4, 16, v20
	v_and_b32_e32 v5, 0xffff0000, v20
	v_pk_add_f32 v[8:9], v[8:9], v[48:49] op_sel_hi:[1,0]
	v_permlane32_swap_b32_e32 v21, v31
	v_mov_b32_e32 v33, v39
	v_lshlrev_b32_e32 v6, 16, v36
	v_and_b32_e32 v7, 0xffff0000, v36
	v_pk_mul_f32 v[4:5], v[8:9], v[4:5]
	v_permlane32_swap_b32_e32 v37, v33
	v_pk_mul_f32 v[4:5], v[4:5], v[6:7]
	v_lshlrev_b32_e32 v6, 16, v21
	v_and_b32_e32 v7, 0xffff0000, v21
	v_pk_add_f32 v[10:11], v[10:11], v[48:49] op_sel_hi:[1,0]
	v_lshlrev_b32_e32 v8, 16, v37
	v_and_b32_e32 v9, 0xffff0000, v37
	v_pk_mul_f32 v[6:7], v[10:11], v[6:7]
	v_cvt_pk_bf16_f32 v4, v4, v5
	v_pk_mul_f32 v[6:7], v[6:7], v[8:9]
	v_pk_add_f32 v[10:11], v[12:13], v[48:49] op_sel_hi:[1,0]
	v_cvt_pk_bf16_f32 v5, v6, v7
	v_lshlrev_b32_e32 v6, 16, v30
	v_and_b32_e32 v7, 0xffff0000, v30
	v_lshlrev_b32_e32 v8, 16, v32
	v_and_b32_e32 v9, 0xffff0000, v32
	v_pk_mul_f32 v[6:7], v[10:11], v[6:7]
	v_pk_add_f32 v[12:13], v[14:15], v[48:49] op_sel_hi:[1,0]
	v_pk_mul_f32 v[6:7], v[6:7], v[8:9]
	v_lshlrev_b32_e32 v8, 16, v31
	v_and_b32_e32 v9, 0xffff0000, v31
	v_lshlrev_b32_e32 v10, 16, v33
	v_and_b32_e32 v11, 0xffff0000, v33
	v_pk_mul_f32 v[8:9], v[12:13], v[8:9]
	v_cvt_pk_bf16_f32 v6, v6, v7
	v_pk_mul_f32 v[8:9], v[8:9], v[10:11]
	v_permlane32_swap_b32_e32 v0, v2
	v_cvt_pk_bf16_f32 v7, v8, v9
	v_lshlrev_b64 v[8:9], 11, v[102:103]
	v_lshl_add_u64 v[8:9], v[104:105], 0, v[8:9]
	v_permlane32_swap_b32_e32 v1, v3
	v_lshl_add_u64 v[8:9], v[8:9], 0, v[94:95]
	v_permlane32_swap_b32_e32 v4, v6
	v_permlane32_swap_b32_e32 v5, v7
	global_store_dwordx4 v[8:9], v[0:3], off
	global_store_dwordx4 v[8:9], v[4:7], off offset:32
	s_barrier
	s_cbranch_scc0 .LBB0_2016
.LBB0_2014:
	s_and_b32 s99, s34, 7
	s_lshl_b32 s99, s99, 7
	s_lshr_b32 s100, s34, 3
	s_or_b32 s99, s99, s100
	s_lshl_b32 s100, s99, 4
	s_ashr_i32 s16, s99, 8
	s_ashr_i32 s17, s16, 31
	v_mov_b32_e32 v0, v207
	s_lshl_b64 s[14:15], s[16:17], 12
	s_and_b32 s6, s100, 0xf80
	s_or_b32 s14, s14, s6
	v_cmp_gt_i32_e32 vcc, s26, v0
	s_and_saveexec_b64 s[18:19], vcc
	s_cbranch_execz .LBB0_2013
	v_ashrrev_i32_e32 v1, 31, v0
	v_lshl_add_u64 v[2:3], s[14:15], 0, v[0:1]
	v_lshlrev_b64 v[2:3], 7, v[2:3]
	v_lshl_add_u64 v[30:31], s[4:5], 0, v[2:3]
	global_load_dwordx4 v[2:5], v[30:31], off
	global_load_dwordx4 v[6:9], v[30:31], off offset:16
	global_load_dwordx4 v[10:13], v[30:31], off offset:32
	global_load_dwordx4 v[14:17], v[30:31], off offset:48
	global_load_dwordx4 v[18:21], v[30:31], off offset:64
	global_load_dwordx4 v[22:25], v[30:31], off offset:80
	global_load_dwordx4 v[26:29], v[30:31], off offset:96
	s_nop 0
	global_load_dwordx4 v[30:33], v[30:31], off offset:112
	s_waitcnt vmcnt(7)
	v_pk_add_f32 v[2:3], v[2:3], 0 op_sel_hi:[1,0]
	s_nop 0
	v_pk_add_f32 v[2:3], v[2:3], v[4:5]
	s_waitcnt vmcnt(6)
	v_pk_add_f32 v[2:3], v[2:3], v[6:7]
	s_nop 0
	v_pk_add_f32 v[2:3], v[2:3], v[8:9]
	s_waitcnt vmcnt(5)
	v_pk_add_f32 v[2:3], v[2:3], v[10:11]
	s_nop 0
	v_pk_add_f32 v[2:3], v[2:3], v[12:13]
	s_waitcnt vmcnt(4)
	v_pk_add_f32 v[2:3], v[2:3], v[14:15]
	s_nop 0
	v_pk_add_f32 v[2:3], v[2:3], v[16:17]
	s_waitcnt vmcnt(3)
	v_pk_add_f32 v[2:3], v[2:3], v[18:19]
	s_nop 0
	v_pk_add_f32 v[2:3], v[2:3], v[20:21]
	s_waitcnt vmcnt(2)
	v_pk_add_f32 v[2:3], v[2:3], v[22:23]
	s_nop 0
	v_pk_add_f32 v[2:3], v[2:3], v[24:25]
	s_waitcnt vmcnt(1)
	v_pk_add_f32 v[2:3], v[2:3], v[26:27]
	s_nop 0
	v_pk_add_f32 v[2:3], v[2:3], v[28:29]
	s_waitcnt vmcnt(0)
	v_pk_add_f32 v[2:3], v[2:3], v[30:31]
	s_nop 0
	v_pk_add_f32 v[2:3], v[2:3], v[32:33]
	s_nop 0
	v_pk_mul_f32 v[2:3], v[2:3], s[8:9] op_sel_hi:[1,0]
	s_nop 0
	v_fma_f32 v1, -v2, v2, v3
	v_max_f32_e32 v1, 0, v1
	v_add_f32_e32 v1, 0x3727c5ac, v1
	v_mul_f32_e32 v3, 0x4b800000, v1
	v_cmp_gt_f32_e32 vcc, s27, v1
	s_nop 1
	v_cndmask_b32_e32 v1, v1, v3, vcc
	v_rsq_f32_e32 v1, v1
	v_lshlrev_b32_e32 v3, 2, v0
	v_mul_f32_e32 v4, 0x45800000, v1
	v_cndmask_b32_e32 v1, v1, v4, vcc
	ds_write2st64_b32 v3, v2, v1 offset1:2
	s_branch .LBB0_2013

.LBB0_2048:
	s_andn2_saveexec_b64 s[2:3], s[6:7]
	s_cbranch_execz .LBB0_2068
	s_mov_b64 s[6:7], exec
	s_branch .LBB0_2065
	buffer_wbl2 sc1
	s_waitcnt lgkmcnt(0)
	s_waitcnt vmcnt(0)
	v_mbcnt_lo_u32_b32 v1, s6, 0
	v_mbcnt_hi_u32_b32 v1, s7, v1
	v_cmp_eq_u32_e32 vcc, 0, v1
	s_and_saveexec_b64 s[8:9], vcc
	s_cbranch_execz .LBB0_2051
	s_bcnt1_i32_b64 s2, s[6:7]
	v_mov_b32_e32 v2, 0xfd2c000
	v_mov_b32_e32 v3, s2
	global_atomic_add v2, v2, v3, s[58:59] offset:1024 sc0

	.amdhsa_kernel _Z8fwd_mega6Paramsi
		.amdhsa_group_segment_fixed_size 65552
		.amdhsa_private_segment_fixed_size 0
		.amdhsa_kernarg_size 456
		.amdhsa_user_sgpr_count 2
		.amdhsa_user_sgpr_dispatch_ptr 0
		.amdhsa_user_sgpr_queue_ptr 0
		.amdhsa_user_sgpr_kernarg_segment_ptr 1
		.amdhsa_user_sgpr_dispatch_id 0
		.amdhsa_user_sgpr_kernarg_preload_length 0
		.amdhsa_user_sgpr_kernarg_preload_offset 0
		.amdhsa_user_sgpr_private_segment_size 0
		.amdhsa_uses_dynamic_stack 0
		.amdhsa_enable_private_segment 0
		.amdhsa_system_sgpr_workgroup_id_x 1
		.amdhsa_system_sgpr_workgroup_id_y 0
		.amdhsa_system_sgpr_workgroup_id_z 0
		.amdhsa_system_sgpr_workgroup_info 0
		.amdhsa_system_vgpr_workitem_id 2
		.amdhsa_next_free_vgpr 256
		.amdhsa_next_free_sgpr 102
		.amdhsa_accum_offset 256
		.amdhsa_reserve_vcc 1
		.amdhsa_float_round_mode_32 0
		.amdhsa_float_round_mode_16_64 0
		.amdhsa_float_denorm_mode_32 3
		.amdhsa_float_denorm_mode_16_64 3
		.amdhsa_dx10_clamp 1
		.amdhsa_ieee_mode 1
		.amdhsa_fp16_overflow 0
		.amdhsa_tg_split 0
		.amdhsa_exception_fp_ieee_invalid_op 0
		.amdhsa_exception_fp_denorm_src 0
		.amdhsa_exception_fp_ieee_div_zero 0
		.amdhsa_exception_fp_ieee_overflow 0
		.amdhsa_exception_fp_ieee_underflow 0
		.amdhsa_exception_fp_ieee_inexact 0
		.amdhsa_exception_int_div_zero 0
	.end_amdhsa_kernel

amdhsa.kernels:
  - .agpr_count:     0
    .args:
      - .offset:         0
        .size:           192
        .value_kind:     by_value
      - .offset:         192
        .size:           4
        .value_kind:     by_value
      - .offset:         200
        .size:           4
        .value_kind:     hidden_block_count_x
      - .offset:         204
        .size:           4
        .value_kind:     hidden_block_count_y
      - .offset:         208
        .size:           4
        .value_kind:     hidden_block_count_z
      - .offset:         212
        .size:           2
        .value_kind:     hidden_group_size_x
      - .offset:         214
        .size:           2
        .value_kind:     hidden_group_size_y
      - .offset:         216
        .size:           2
        .value_kind:     hidden_group_size_z
      - .offset:         218
        .size:           2
        .value_kind:     hidden_remainder_x
      - .offset:         220
        .size:           2
        .value_kind:     hidden_remainder_y
      - .offset:         222
        .size:           2
        .value_kind:     hidden_remainder_z
      - .offset:         240
        .size:           8
        .value_kind:     hidden_global_offset_x
      - .offset:         248
        .size:           8
        .value_kind:     hidden_global_offset_y
      - .offset:         256
        .size:           8
        .value_kind:     hidden_global_offset_z
      - .offset:         264
        .size:           2
        .value_kind:     hidden_grid_dims
      - .offset:         288
        .size:           8
        .value_kind:     hidden_multigrid_sync_arg
    .group_segment_fixed_size: 65552
    .kernarg_segment_align: 8
    .kernarg_segment_size: 456
    .language:       OpenCL C
    .language_version:
      - 2
      - 0
    .max_flat_workgroup_size: 256
    .name:           _Z8fwd_mega6Paramsi
    .private_segment_fixed_size: 0
    .sgpr_count:     108
    .sgpr_spill_count: 11
    .symbol:         _Z8fwd_mega6Paramsi.kd
    .uniform_work_group_size: 1
    .uses_dynamic_stack: false
    .vgpr_count:     256
    .vgpr_spill_count: 0
    .wavefront_size: 64
